# hs + differential-attention unit prologue: Q fragment loads issued before the six first-tile DMA loads, wait for Q relaxed from vmcnt(0) to vmcnt(3)
# speedup vs baseline: 1.0008x; 1.0008x over previous
.LBB0_1088:
	s_lshl_b32 s3, s41, 7
	s_and_b32 s3, s3, 0x380
	s_and_b32 s49, s40, 1
	s_lshl_b32 s51, s3, 1
	s_add_u32 s45, s80, s51
	s_addc_u32 s50, s81, 0
	s_lshl_b32 s3, s49, 7
	s_add_u32 s3, s45, s3
	s_addc_u32 s5, s50, 0
	s_ashr_i32 s24, s41, 3
	s_add_u32 s28, s36, s51
	s_addc_u32 s29, s37, 0
	s_ashr_i32 s25, s24, 31
	v_readfirstlane_b32 s52, v206
	s_lshl_b64 s[6:7], s[24:25], 13
	s_lshl_b32 s25, s42, 8
	s_lshr_b32 s48, s52, 6
	s_ashr_i32 s26, s25, 31
	s_add_u32 s6, s6, s25
	s_addc_u32 s7, s7, s26
	s_lshl_b32 s55, s48, 5
	s_add_u32 s43, s6, s55
	s_addc_u32 s44, s7, 0
	s_mul_i32 s6, s44, 0x1800
	s_mul_hi_u32 s7, s43, 0x1800
	s_add_i32 s7, s7, s6
	s_mul_i32 s6, s43, 0x1800
	s_add_u32 s6, s3, s6
	s_addc_u32 s7, s5, s7
	s_mul_i32 s54, s24, 0x3000000
	s_mul_hi_i32 s53, s24, 0x3000000
	s_add_u32 s26, s3, s54
	s_addc_u32 s27, s5, s53
	v_mov_b32_e32 v173, v1
	v_lshl_add_u64 v[2:3], s[26:27], 0, v[172:173]
	s_lshl_b32 s26, s48, 4
	s_mov_b32 s27, s4
	v_lshl_add_u64 v[4:5], v[2:3], 0, s[26:27]
	s_add_u32 s26, s28, s54
	s_addc_u32 s27, s29, s53
	s_lshr_b32 s3, s52, 2
	v_and_or_b32 v0, s3, 48, v187
	v_mul_u32_u24_e32 v0, 0xc00, v0
	v_lshlrev_b32_e32 v180, 1, v0
	v_mov_b32_e32 v181, v1
	v_lshl_add_u64 v[2:3], s[26:27], 0, v[180:181]
	s_and_b32 s26, s3, 0x3fffffc0
	s_lshl_b32 s3, s48, 10
	s_cmp_lg_u32 0, -1
	s_mov_b32 s27, s4
	s_cselect_b32 s5, 0, 0
	v_lshl_add_u64 v[178:179], v[4:5], 0, s[8:9]
	v_lshl_add_u64 v[2:3], v[2:3], 0, s[26:27]
	v_mov_b32_e32 v175, v1
	s_add_i32 s52, s3, s5
	global_load_dwordx4 v[116:119], v196, s[6:7] offset:96
	global_load_dwordx4 v[120:123], v196, s[6:7] offset:64
	global_load_dwordx4 v[124:127], v196, s[6:7] offset:32
	global_load_dwordx4 v[128:131], v196, s[6:7]
	s_mov_b32 s5, m0
	s_mov_b32 m0, s52
	s_nop 0
	global_load_lds_dwordx4 v[178:179], off
	s_mov_b32 m0, s5
	v_lshl_add_u64 v[2:3], v[2:3], 0, v[174:175]
	s_add_i32 s53, s52, 0x8000
	s_mov_b32 s5, m0
	s_mov_b32 m0, s53
	s_nop 0
	global_load_lds_dwordx4 v[2:3], off
	s_mov_b32 m0, s5
	v_lshl_add_u64 v[6:7], v[2:3], 0, s[10:11]
	s_add_i32 s5, s52, 0xa000
	s_mov_b32 s27, m0
	s_mov_b32 m0, s5
	s_nop 0
	global_load_lds_dwordx4 v[6:7], off
	s_mov_b32 m0, s27
	v_lshl_add_u64 v[4:5], v[4:5], 0, s[12:13]
	s_add_i32 s5, s52, 0x2000
	s_mov_b32 s27, m0
	s_mov_b32 m0, s5
	s_nop 0
	global_load_lds_dwordx4 v[4:5], off
	s_mov_b32 m0, s27
	v_lshl_add_u64 v[4:5], v[2:3], 0, s[14:15]
	s_add_i32 s5, s52, 0xc000
	s_mov_b32 s27, m0
	s_mov_b32 m0, s5
	s_nop 0
	global_load_lds_dwordx4 v[4:5], off
	s_mov_b32 m0, s27
	v_lshl_add_u64 v[4:5], v[2:3], 0, s[16:17]
	s_add_i32 s5, s52, 0xe000
	s_mov_b32 s27, m0
	s_mov_b32 m0, s5
	s_nop 0
	global_load_lds_dwordx4 v[4:5], off
	s_mov_b32 m0, s27
	s_add_i32 s5, s25, 0x100
	s_add_i32 s55, s55, s25
	s_ashr_i32 s54, s5, 6
	s_ashr_i32 s25, s55, 6
	s_cmp_gt_i32 s25, 0
	s_mov_b32 s27, 0
	s_cselect_b64 s[28:29], -1, 0
	s_cmp_lt_i32 s25, 1
	s_waitcnt vmcnt(3)
	s_cbranch_scc1 .LBB0_1134
	s_cmp_gt_i32 s54, 1
	s_mov_b64 s[6:7], -1
	s_cbranch_scc1 .LBB0_1091
	s_waitcnt vmcnt(0) lgkmcnt(0)
	s_barrier
	s_mov_b64 s[6:7], 0

.LBB0_1134:
	s_waitcnt vmcnt(0)
	s_nop 0
	s_nop 0
	s_nop 0
	s_nop 0
	s_nop 0
	s_nop 0
	s_nop 0
	s_nop 0
	s_nop 0
	s_nop 0
	s_nop 0
	s_nop 0
	s_nop 0
	s_nop 0
	s_nop 0
	v_mov_b32_e32 v14, v1
	v_mov_b32_e32 v15, v1
	v_mov_b32_e32 v0, v1
	v_mov_b32_e32 v2, v1
	v_mov_b32_e32 v3, v1
	v_mov_b32_e32 v4, v1
	v_mov_b32_e32 v5, v1
	v_mov_b32_e32 v6, v1
	v_mov_b32_e32 v7, v1
	v_mov_b32_e32 v8, v1
	v_mov_b32_e32 v9, v1
	v_mov_b32_e32 v10, v1
	v_mov_b32_e32 v11, v1
	v_mov_b32_e32 v12, v1
	v_mov_b32_e32 v13, v1
	v_mov_b64_e32 v[66:67], v[14:15]
	v_mov_b64_e32 v[50:51], v[14:15]
	v_mov_b64_e32 v[34:35], v[14:15]
	v_mov_b64_e32 v[64:65], v[12:13]
	v_mov_b64_e32 v[62:63], v[10:11]
	v_mov_b64_e32 v[60:61], v[8:9]
	v_mov_b64_e32 v[58:59], v[6:7]
	v_mov_b64_e32 v[56:57], v[4:5]
	v_mov_b64_e32 v[54:55], v[2:3]
	v_mov_b64_e32 v[52:53], v[0:1]
	v_mov_b64_e32 v[48:49], v[12:13]
	v_mov_b64_e32 v[46:47], v[10:11]
	v_mov_b64_e32 v[44:45], v[8:9]
	v_mov_b64_e32 v[42:43], v[6:7]
	v_mov_b64_e32 v[40:41], v[4:5]
	v_mov_b64_e32 v[38:39], v[2:3]
	v_mov_b64_e32 v[36:37], v[0:1]
	v_mov_b64_e32 v[32:33], v[12:13]
	v_mov_b64_e32 v[30:31], v[10:11]
	v_mov_b64_e32 v[28:29], v[8:9]
	v_mov_b64_e32 v[26:27], v[6:7]
	v_mov_b64_e32 v[24:25], v[4:5]
	v_mov_b64_e32 v[22:23], v[2:3]
	v_mov_b64_e32 v[20:21], v[0:1]
	v_mov_b64_e32 v[18:19], v[14:15]
	v_mov_b32_e32 v175, 0
	v_mov_b32_e32 v135, 0
	v_mov_b32_e32 v134, 0
	v_mov_b32_e32 v133, 0
	v_mov_b32_e32 v132, 0
	v_mov_b32_e32 v139, 0
	v_mov_b32_e32 v138, 0
	v_mov_b32_e32 v137, 0
	v_mov_b32_e32 v136, 0
	v_mov_b32_e32 v143, 0
	v_mov_b32_e32 v142, 0
	v_mov_b32_e32 v141, 0
	v_mov_b32_e32 v140, 0
	v_mov_b32_e32 v147, 0
	v_mov_b32_e32 v146, 0
	v_mov_b32_e32 v145, 0
	v_mov_b32_e32 v144, 0
	v_mov_b32_e32 v173, 0
	v_mov_b64_e32 v[16:17], v[12:13]
	v_mov_b64_e32 v[14:15], v[10:11]
	v_mov_b64_e32 v[12:13], v[8:9]
	v_mov_b64_e32 v[10:11], v[6:7]
	v_mov_b64_e32 v[8:9], v[4:5]
	v_mov_b64_e32 v[6:7], v[2:3]
	v_mov_b64_e32 v[4:5], v[0:1]
	s_andn2_b64 vcc, exec, s[28:29]
	s_cbranch_vccz .LBB0_1107
	s_branch .LBB0_1108
